# plus: sequence-DFT phase: each latent 256x256 unit split over two workgroups (upper/lower 128 rows) using the 64 workgroups that were idle in that phase
# speedup vs baseline: 1.0367x; 1.0025x over previous
.LBB0_501:
	s_and_b64 vcc, exec, s[8:9]
	s_cbranch_vccnz .LBB0_503
	s_movk_i32 s16, 0x200
	s_movk_i32 s15, 0x200
	s_mov_b32 s6, s39
	s_mov_b32 s98, 0
	s_branch .LBB0_504
.LBB0_503:
	s_movk_i32 s15, 0x400
	s_movk_i32 s16, 0x800
	s_mov_b32 s6, s68
	v_readlane_b32 s99, v254, 55
	s_mov_b32 s98, 0
	s_cmpk_lg_u32 s99, 0x100
	s_cbranch_scc1 .Ld2_nohalf
	s_mov_b32 s98, 1
	s_cmpk_lt_u32 s68, 0xc0
	s_cbranch_scc1 .Ld2_nohalf
	s_sub_u32 s6, s68, 0xc0
	s_mov_b32 s98, 2
.Ld2_nohalf:
.LBB0_504:
	s_xor_b64 s[4:5], s[8:9], -1
	s_and_b64 s[8:9], exec, s[8:9]
	s_mov_b32 s7, 0x50f8000
	s_cselect_b32 s7, s7, 0x50b8000
	s_add_u32 s8, s80, s7
	v_mbcnt_lo_u32_b32 v5, -1, 0
	v_mbcnt_hi_u32_b32 v5, -1, v5
	s_addc_u32 s9, s81, 0
	v_add_u32_e32 v0, s75, v5
	s_and_b64 vcc, exec, s[4:5]
	v_readfirstlane_b32 s14, v0
	s_cbranch_vccz .LBB0_510
	s_mov_b64 s[12:13], 0
	s_cmpk_lt_i32 s6, 0x80
	s_mov_b64 s[10:11], 0
	s_cbranch_scc0 .LBB0_507
	s_ashr_i32 s7, s6, 31
	s_lshl_b64 s[10:11], s[6:7], 18
	s_add_u32 s22, s72, s10
	s_addc_u32 s23, s73, s11
	s_mov_b64 s[10:11], -1

.LBB0_526:
	s_add_i32 s34, s24, 2
	s_add_u32 s35, s22, 0x80
	s_addc_u32 s25, s23, 0
	s_add_i32 s53, 0, 0x10000
	s_cmp_eq_u32 s48, s24
	s_cselect_b32 s25, s26, s25
	s_cselect_b32 s24, s27, s35
	s_cselect_b32 s57, s28, s31
	s_cselect_b32 s56, s29, s30
	s_add_i32 s35, 0, 0x14000
	v_add_u32_e32 v154, s53, v140
	v_add_u32_e32 v170, s35, v140
	ds_read_b128 v[142:145], v154
	ds_read_b128 v[146:149], v154 offset:1024
	ds_read_b128 v[150:153], v154 offset:2048
	ds_read_b128 v[154:157], v154 offset:3072
	ds_read_b128 v[158:161], v170
	ds_read_b128 v[162:165], v170 offset:1024
	ds_read_b128 v[166:169], v170 offset:2048
	ds_read_b128 v[170:173], v170 offset:3072
	v_lshl_add_u64 v[206:207], s[22:23], 0, v[138:139]
	s_add_i32 m0, s41, 0xc000
	ds_read_b128 v[174:177], v141
	ds_read_b128 v[178:181], v141 offset:1024
	ds_read_b128 v[182:185], v141 offset:2048
	ds_read_b128 v[186:189], v141 offset:3072
	ds_read_b128 v[190:193], v141 offset:4096
	ds_read_b128 v[194:197], v141 offset:5120
	ds_read_b128 v[198:201], v141 offset:6144
	ds_read_b128 v[202:205], v141 offset:7168
	global_load_lds_dwordx4 v[206:207], off
	v_lshl_add_u64 v[206:207], s[22:23], 0, v[136:137]
	s_add_i32 m0, s41, 0xe000
	s_nop 0
	global_load_lds_dwordx4 v[206:207], off
	s_waitcnt vmcnt(8)
	s_waitcnt lgkmcnt(0)
	s_barrier
	s_setprio 1
	s_waitcnt lgkmcnt(0)
	s_bitcmp1_b32 s98, 1
	s_cbranch_scc1 .Ld2_sk_0
	v_mfma_f32_16x16x32_bf16 v[126:129], v[142:145], v[174:177], v[126:129]
	v_mfma_f32_16x16x32_bf16 v[122:125], v[150:153], v[174:177], v[122:125]
	v_mfma_f32_16x16x32_bf16 v[118:121], v[142:145], v[182:185], v[118:121]
	v_mfma_f32_16x16x32_bf16 v[110:113], v[150:153], v[182:185], v[110:113]
	v_mfma_f32_16x16x32_bf16 v[102:105], v[142:145], v[190:193], v[102:105]
	v_mfma_f32_16x16x32_bf16 v[94:97], v[150:153], v[190:193], v[94:97]
	v_mfma_f32_16x16x32_bf16 v[86:89], v[142:145], v[198:201], v[86:89]
	v_mfma_f32_16x16x32_bf16 v[78:81], v[150:153], v[198:201], v[78:81]
	v_mfma_f32_16x16x32_bf16 v[126:129], v[146:149], v[178:181], v[126:129]
	v_mfma_f32_16x16x32_bf16 v[122:125], v[154:157], v[178:181], v[122:125]
	v_mfma_f32_16x16x32_bf16 v[118:121], v[146:149], v[186:189], v[118:121]
	v_mfma_f32_16x16x32_bf16 v[110:113], v[154:157], v[186:189], v[110:113]
	v_mfma_f32_16x16x32_bf16 v[102:105], v[146:149], v[194:197], v[102:105]
	v_mfma_f32_16x16x32_bf16 v[94:97], v[154:157], v[194:197], v[94:97]
	v_mfma_f32_16x16x32_bf16 v[86:89], v[146:149], v[202:205], v[86:89]
	v_mfma_f32_16x16x32_bf16 v[78:81], v[154:157], v[202:205], v[78:81]
	s_setprio 0
	s_setprio 1
	v_mfma_f32_16x16x32_bf16 v[114:117], v[158:161], v[174:177], v[114:117]
	v_mfma_f32_16x16x32_bf16 v[106:109], v[166:169], v[174:177], v[106:109]
	v_mfma_f32_16x16x32_bf16 v[98:101], v[158:161], v[182:185], v[98:101]
	v_mfma_f32_16x16x32_bf16 v[90:93], v[166:169], v[182:185], v[90:93]
	v_mfma_f32_16x16x32_bf16 v[82:85], v[158:161], v[190:193], v[82:85]
	v_mfma_f32_16x16x32_bf16 v[74:77], v[166:169], v[190:193], v[74:77]
	v_mfma_f32_16x16x32_bf16 v[70:73], v[158:161], v[198:201], v[70:73]
	v_mfma_f32_16x16x32_bf16 v[66:69], v[166:169], v[198:201], v[66:69]
	v_mfma_f32_16x16x32_bf16 v[114:117], v[162:165], v[178:181], v[114:117]
	v_mfma_f32_16x16x32_bf16 v[106:109], v[170:173], v[178:181], v[106:109]
	v_mfma_f32_16x16x32_bf16 v[98:101], v[162:165], v[186:189], v[98:101]
	v_mfma_f32_16x16x32_bf16 v[90:93], v[170:173], v[186:189], v[90:93]
	v_mfma_f32_16x16x32_bf16 v[82:85], v[162:165], v[194:197], v[82:85]
	v_mfma_f32_16x16x32_bf16 v[74:77], v[170:173], v[194:197], v[74:77]
	v_mfma_f32_16x16x32_bf16 v[70:73], v[162:165], v[202:205], v[70:73]
	v_mfma_f32_16x16x32_bf16 v[66:69], v[170:173], v[202:205], v[66:69]
.Ld2_sk_0:
	s_setprio 0
	s_barrier
	s_add_i32 s53, s53, s40
	v_lshl_add_u64 v[206:207], s[56:57], 0, v[0:1]
	s_mov_b32 m0, s53
	ds_read_b128 v[174:177], v141 offset:16384
	ds_read_b128 v[178:181], v141 offset:17408
	ds_read_b128 v[182:185], v141 offset:18432
	ds_read_b128 v[186:189], v141 offset:19456
	ds_read_b128 v[190:193], v141 offset:20480
	ds_read_b128 v[194:197], v141 offset:21504
	ds_read_b128 v[198:201], v141 offset:22528
	ds_read_b128 v[202:205], v141 offset:23552
	global_load_lds_dwordx4 v[206:207], off
	s_add_i32 m0, s53, 0x2000
	v_lshl_add_u64 v[208:209], s[56:57], 0, v[134:135]
	s_add_u32 s56, s56, s7
	s_addc_u32 s57, s57, 0
	s_add_i32 s35, s35, s40
	global_load_lds_dwordx4 v[208:209], off
	v_lshl_add_u64 v[210:211], s[56:57], 0, v[0:1]
	s_mov_b32 m0, s35
	v_lshl_add_u64 v[212:213], s[56:57], 0, v[134:135]
	global_load_lds_dwordx4 v[210:211], off
	s_add_i32 m0, s35, 0x2000
	v_lshl_add_u64 v[214:215], s[24:25], 0, v[130:131]
	global_load_lds_dwordx4 v[212:213], off
	s_mov_b32 m0, s41
	v_lshl_add_u64 v[216:217], s[24:25], 0, v[132:133]
	global_load_lds_dwordx4 v[214:215], off
	s_mov_b32 m0, s42
	s_nop 0
	global_load_lds_dwordx4 v[216:217], off
	s_waitcnt vmcnt(8)
	s_waitcnt lgkmcnt(0)
	s_barrier
	s_setprio 1
	s_waitcnt lgkmcnt(0)
	s_bitcmp1_b32 s98, 0
	s_cbranch_scc1 .Ld2_sk_1
	v_mfma_f32_16x16x32_bf16 v[62:65], v[142:145], v[174:177], v[62:65]
	v_mfma_f32_16x16x32_bf16 v[58:61], v[150:153], v[174:177], v[58:61]
	v_mfma_f32_16x16x32_bf16 v[54:57], v[142:145], v[182:185], v[54:57]
	v_mfma_f32_16x16x32_bf16 v[46:49], v[150:153], v[182:185], v[46:49]
	v_mfma_f32_16x16x32_bf16 v[38:41], v[142:145], v[190:193], v[38:41]
	v_mfma_f32_16x16x32_bf16 v[30:33], v[150:153], v[190:193], v[30:33]
	v_mfma_f32_16x16x32_bf16 v[22:25], v[142:145], v[198:201], v[22:25]
	v_mfma_f32_16x16x32_bf16 v[14:17], v[150:153], v[198:201], v[14:17]
	v_mfma_f32_16x16x32_bf16 v[62:65], v[146:149], v[178:181], v[62:65]
	v_mfma_f32_16x16x32_bf16 v[58:61], v[154:157], v[178:181], v[58:61]
	v_mfma_f32_16x16x32_bf16 v[54:57], v[146:149], v[186:189], v[54:57]
	v_mfma_f32_16x16x32_bf16 v[46:49], v[154:157], v[186:189], v[46:49]
	v_mfma_f32_16x16x32_bf16 v[38:41], v[146:149], v[194:197], v[38:41]
	v_mfma_f32_16x16x32_bf16 v[30:33], v[154:157], v[194:197], v[30:33]
	v_mfma_f32_16x16x32_bf16 v[22:25], v[146:149], v[202:205], v[22:25]
	v_mfma_f32_16x16x32_bf16 v[14:17], v[154:157], v[202:205], v[14:17]
	s_setprio 0
	s_setprio 1
	v_mfma_f32_16x16x32_bf16 v[50:53], v[158:161], v[174:177], v[50:53]
	v_mfma_f32_16x16x32_bf16 v[42:45], v[166:169], v[174:177], v[42:45]
	v_mfma_f32_16x16x32_bf16 v[34:37], v[158:161], v[182:185], v[34:37]
	v_mfma_f32_16x16x32_bf16 v[26:29], v[166:169], v[182:185], v[26:29]
	v_mfma_f32_16x16x32_bf16 v[18:21], v[158:161], v[190:193], v[18:21]
	v_mfma_f32_16x16x32_bf16 v[10:13], v[166:169], v[190:193], v[10:13]
	v_mfma_f32_16x16x32_bf16 v[6:9], v[158:161], v[198:201], v[6:9]
	v_mfma_f32_16x16x32_bf16 v[2:5], v[166:169], v[198:201], v[2:5]
	v_mfma_f32_16x16x32_bf16 v[50:53], v[162:165], v[178:181], v[50:53]
	v_mfma_f32_16x16x32_bf16 v[42:45], v[170:173], v[178:181], v[42:45]
	v_mfma_f32_16x16x32_bf16 v[34:37], v[162:165], v[186:189], v[34:37]
	v_mfma_f32_16x16x32_bf16 v[26:29], v[170:173], v[186:189], v[26:29]
	v_mfma_f32_16x16x32_bf16 v[18:21], v[162:165], v[194:197], v[18:21]
	v_mfma_f32_16x16x32_bf16 v[10:13], v[170:173], v[194:197], v[10:13]
	v_mfma_f32_16x16x32_bf16 v[6:9], v[162:165], v[202:205], v[6:9]
	v_mfma_f32_16x16x32_bf16 v[2:5], v[170:173], v[202:205], v[2:5]
.Ld2_sk_1:
	s_setprio 0
	s_barrier
	s_add_i32 s35, 0, 0x18000
	s_add_i32 s53, 0, 0x1c000
	v_add_u32_e32 v154, s35, v140
	v_add_u32_e32 v170, s53, v140
	ds_read_b128 v[142:145], v154
	ds_read_b128 v[146:149], v154 offset:1024
	ds_read_b128 v[150:153], v154 offset:2048
	ds_read_b128 v[154:157], v154 offset:3072
	ds_read_b128 v[158:161], v170
	ds_read_b128 v[162:165], v170 offset:1024
	ds_read_b128 v[166:169], v170 offset:2048
	ds_read_b128 v[170:173], v170 offset:3072
	s_add_u32 s24, s24, s68
	s_addc_u32 s25, s25, 0
	s_mov_b32 m0, s43
	v_lshl_add_u64 v[218:219], s[24:25], 0, v[130:131]
	ds_read_b128 v[174:177], v141 offset:32768
	ds_read_b128 v[178:181], v141 offset:33792
	ds_read_b128 v[182:185], v141 offset:34816
	ds_read_b128 v[186:189], v141 offset:35840
	ds_read_b128 v[190:193], v141 offset:36864
	ds_read_b128 v[194:197], v141 offset:37888
	ds_read_b128 v[198:201], v141 offset:38912
	ds_read_b128 v[202:205], v141 offset:39936
	global_load_lds_dwordx4 v[218:219], off
	v_lshl_add_u64 v[218:219], s[24:25], 0, v[132:133]
	s_mov_b32 m0, s44
	s_nop 0
	global_load_lds_dwordx4 v[218:219], off
	s_waitcnt vmcnt(8)
	s_waitcnt lgkmcnt(0)
	s_barrier
	s_setprio 1
	s_waitcnt lgkmcnt(0)
	s_bitcmp1_b32 s98, 1
	s_cbranch_scc1 .Ld2_sk_2
	v_mfma_f32_16x16x32_bf16 v[126:129], v[142:145], v[174:177], v[126:129]
	v_mfma_f32_16x16x32_bf16 v[122:125], v[150:153], v[174:177], v[122:125]
	v_mfma_f32_16x16x32_bf16 v[118:121], v[142:145], v[182:185], v[118:121]
	v_mfma_f32_16x16x32_bf16 v[110:113], v[150:153], v[182:185], v[110:113]
	v_mfma_f32_16x16x32_bf16 v[102:105], v[142:145], v[190:193], v[102:105]
	v_mfma_f32_16x16x32_bf16 v[94:97], v[150:153], v[190:193], v[94:97]
	v_mfma_f32_16x16x32_bf16 v[86:89], v[142:145], v[198:201], v[86:89]
	v_mfma_f32_16x16x32_bf16 v[78:81], v[150:153], v[198:201], v[78:81]
	v_mfma_f32_16x16x32_bf16 v[126:129], v[146:149], v[178:181], v[126:129]
	v_mfma_f32_16x16x32_bf16 v[122:125], v[154:157], v[178:181], v[122:125]
	v_mfma_f32_16x16x32_bf16 v[118:121], v[146:149], v[186:189], v[118:121]
	v_mfma_f32_16x16x32_bf16 v[110:113], v[154:157], v[186:189], v[110:113]
	v_mfma_f32_16x16x32_bf16 v[102:105], v[146:149], v[194:197], v[102:105]
	v_mfma_f32_16x16x32_bf16 v[94:97], v[154:157], v[194:197], v[94:97]
	v_mfma_f32_16x16x32_bf16 v[86:89], v[146:149], v[202:205], v[86:89]
	v_mfma_f32_16x16x32_bf16 v[78:81], v[154:157], v[202:205], v[78:81]
	s_setprio 0
	s_setprio 1
	v_mfma_f32_16x16x32_bf16 v[114:117], v[158:161], v[174:177], v[114:117]
	v_mfma_f32_16x16x32_bf16 v[106:109], v[166:169], v[174:177], v[106:109]
	v_mfma_f32_16x16x32_bf16 v[98:101], v[158:161], v[182:185], v[98:101]
	v_mfma_f32_16x16x32_bf16 v[90:93], v[166:169], v[182:185], v[90:93]
	v_mfma_f32_16x16x32_bf16 v[82:85], v[158:161], v[190:193], v[82:85]
	v_mfma_f32_16x16x32_bf16 v[74:77], v[166:169], v[190:193], v[74:77]
	v_mfma_f32_16x16x32_bf16 v[70:73], v[158:161], v[198:201], v[70:73]
	v_mfma_f32_16x16x32_bf16 v[66:69], v[166:169], v[198:201], v[66:69]
	v_mfma_f32_16x16x32_bf16 v[114:117], v[162:165], v[178:181], v[114:117]
	v_mfma_f32_16x16x32_bf16 v[106:109], v[170:173], v[178:181], v[106:109]
	v_mfma_f32_16x16x32_bf16 v[98:101], v[162:165], v[186:189], v[98:101]
	v_mfma_f32_16x16x32_bf16 v[90:93], v[170:173], v[186:189], v[90:93]
	v_mfma_f32_16x16x32_bf16 v[82:85], v[162:165], v[194:197], v[82:85]
	v_mfma_f32_16x16x32_bf16 v[74:77], v[170:173], v[194:197], v[74:77]
	v_mfma_f32_16x16x32_bf16 v[70:73], v[162:165], v[202:205], v[70:73]
	v_mfma_f32_16x16x32_bf16 v[66:69], v[170:173], v[202:205], v[66:69]
.Ld2_sk_2:
	s_setprio 0
	s_barrier
	s_add_i32 s24, s35, s40
	v_lshl_add_u64 v[206:207], v[206:207], 0, s[76:77]
	s_mov_b32 m0, s24
	ds_read_b128 v[174:177], v141 offset:49152
	ds_read_b128 v[178:181], v141 offset:50176
	ds_read_b128 v[182:185], v141 offset:51200
	ds_read_b128 v[186:189], v141 offset:52224
	ds_read_b128 v[190:193], v141 offset:53248
	ds_read_b128 v[194:197], v141 offset:54272
	ds_read_b128 v[198:201], v141 offset:55296
	ds_read_b128 v[202:205], v141 offset:56320
	global_load_lds_dwordx4 v[206:207], off
	v_lshl_add_u64 v[206:207], v[208:209], 0, s[76:77]
	s_add_i32 m0, s24, 0x2000
	s_add_i32 s24, s53, s40
	global_load_lds_dwordx4 v[206:207], off
	v_lshl_add_u64 v[206:207], v[210:211], 0, s[76:77]
	s_mov_b32 m0, s24
	s_nop 0
	global_load_lds_dwordx4 v[206:207], off
	v_lshl_add_u64 v[206:207], v[212:213], 0, s[76:77]
	s_add_i32 m0, s24, 0x2000
	s_nop 0
	global_load_lds_dwordx4 v[206:207], off
	v_lshl_add_u64 v[206:207], v[214:215], 0, s[76:77]
	s_mov_b32 m0, s46
	s_nop 0
	global_load_lds_dwordx4 v[206:207], off
	v_lshl_add_u64 v[206:207], v[216:217], 0, s[76:77]
	s_mov_b32 m0, s47
	s_nop 0
	global_load_lds_dwordx4 v[206:207], off
	s_waitcnt vmcnt(8)
	s_waitcnt lgkmcnt(0)
	s_barrier
	s_setprio 1
	s_waitcnt lgkmcnt(0)
	s_bitcmp1_b32 s98, 0
	s_cbranch_scc1 .Ld2_sk_3
	v_mfma_f32_16x16x32_bf16 v[62:65], v[142:145], v[174:177], v[62:65]
	v_mfma_f32_16x16x32_bf16 v[58:61], v[150:153], v[174:177], v[58:61]
	v_mfma_f32_16x16x32_bf16 v[54:57], v[142:145], v[182:185], v[54:57]
	v_mfma_f32_16x16x32_bf16 v[46:49], v[150:153], v[182:185], v[46:49]
	v_mfma_f32_16x16x32_bf16 v[38:41], v[142:145], v[190:193], v[38:41]
	v_mfma_f32_16x16x32_bf16 v[30:33], v[150:153], v[190:193], v[30:33]
	v_mfma_f32_16x16x32_bf16 v[22:25], v[142:145], v[198:201], v[22:25]
	v_mfma_f32_16x16x32_bf16 v[14:17], v[150:153], v[198:201], v[14:17]
	v_mfma_f32_16x16x32_bf16 v[62:65], v[146:149], v[178:181], v[62:65]
	v_mfma_f32_16x16x32_bf16 v[58:61], v[154:157], v[178:181], v[58:61]
	v_mfma_f32_16x16x32_bf16 v[54:57], v[146:149], v[186:189], v[54:57]
	v_mfma_f32_16x16x32_bf16 v[46:49], v[154:157], v[186:189], v[46:49]
	v_mfma_f32_16x16x32_bf16 v[38:41], v[146:149], v[194:197], v[38:41]
	v_mfma_f32_16x16x32_bf16 v[30:33], v[154:157], v[194:197], v[30:33]
	v_mfma_f32_16x16x32_bf16 v[22:25], v[146:149], v[202:205], v[22:25]
	v_mfma_f32_16x16x32_bf16 v[14:17], v[154:157], v[202:205], v[14:17]
	s_setprio 0
	s_setprio 1
	v_mfma_f32_16x16x32_bf16 v[50:53], v[158:161], v[174:177], v[50:53]
	v_mfma_f32_16x16x32_bf16 v[42:45], v[166:169], v[174:177], v[42:45]
	v_mfma_f32_16x16x32_bf16 v[34:37], v[158:161], v[182:185], v[34:37]
	v_mfma_f32_16x16x32_bf16 v[26:29], v[166:169], v[182:185], v[26:29]
	v_mfma_f32_16x16x32_bf16 v[18:21], v[158:161], v[190:193], v[18:21]
	v_mfma_f32_16x16x32_bf16 v[10:13], v[166:169], v[190:193], v[10:13]
	v_mfma_f32_16x16x32_bf16 v[6:9], v[158:161], v[198:201], v[6:9]
	v_mfma_f32_16x16x32_bf16 v[2:5], v[166:169], v[198:201], v[2:5]
	v_mfma_f32_16x16x32_bf16 v[50:53], v[162:165], v[178:181], v[50:53]
	v_mfma_f32_16x16x32_bf16 v[42:45], v[170:173], v[178:181], v[42:45]
	v_mfma_f32_16x16x32_bf16 v[34:37], v[162:165], v[186:189], v[34:37]
	v_mfma_f32_16x16x32_bf16 v[26:29], v[170:173], v[186:189], v[26:29]
	v_mfma_f32_16x16x32_bf16 v[18:21], v[162:165], v[194:197], v[18:21]
	v_mfma_f32_16x16x32_bf16 v[10:13], v[170:173], v[194:197], v[10:13]
	v_mfma_f32_16x16x32_bf16 v[6:9], v[162:165], v[202:205], v[6:9]
	v_mfma_f32_16x16x32_bf16 v[2:5], v[170:173], v[202:205], v[2:5]
.Ld2_sk_3:
	s_setprio 0
	s_barrier
	s_add_u32 s30, s30, 0x100
	s_addc_u32 s31, s31, 0
	s_add_u32 s22, s22, 0x100
	s_addc_u32 s23, s23, 0
	s_cmp_ge_u32 s34, s45
	s_mov_b32 s24, s34
	s_cbranch_scc0 .LBB0_526
	s_and_b64 vcc, exec, s[12:13]
	s_cbranch_vccz .LBB0_529
	s_barrier

.LBB0_539:
	v_mbcnt_lo_u32_b32 v142, -1, 0
	v_mbcnt_hi_u32_b32 v142, -1, v142
	s_and_b32 s61, s15, 0xffff
	v_and_or_b32 v143, v142, 15, s64
	v_lshrrev_b32_e32 v142, 1, v142
	v_and_or_b32 v142, v142, 24, s88
	v_mad_u64_u32 v[142:143], s[22:23], v143, s49, v[142:143]
	s_mov_b32 s60, s14
	v_lshlrev_b32_e32 v143, 1, v142
	v_cvt_pk_bf16_f32 v114, v114, v115
	s_lshl_b32 s22, s49, 5
	v_cvt_pk_bf16_f32 v115, v116, v117
	v_cvt_pk_bf16_f32 v116, v106, v107
	v_cvt_pk_bf16_f32 v117, v108, v109
	s_bitcmp1_b32 s98, 1
	s_cbranch_scc1 .Ld2_ss_0
	buffer_store_dwordx4 v[114:117], v143, s[60:63], 0 offen offset:256 nt sc1
.Ld2_ss_0:
	v_cvt_pk_bf16_f32 v98, v98, v99
	v_cvt_pk_bf16_f32 v126, v126, v127
	v_cvt_pk_bf16_f32 v127, v128, v129
	v_cvt_pk_bf16_f32 v128, v122, v123
	v_cvt_pk_bf16_f32 v129, v124, v125
	s_nop 1
	v_add_u32_e32 v114, s22, v143
	s_bitcmp1_b32 s98, 1
	s_cbranch_scc1 .Ld2_ss_1
	buffer_store_dwordx4 v[126:129], v143, s[60:63], 0 offen nt sc1
.Ld2_ss_1:
	v_cvt_pk_bf16_f32 v99, v100, v101
	v_cvt_pk_bf16_f32 v100, v90, v91
	v_cvt_pk_bf16_f32 v101, v92, v93
	s_bitcmp1_b32 s98, 1
	s_cbranch_scc1 .Ld2_ss_2
	buffer_store_dwordx4 v[98:101], v114, s[60:63], 0 offen offset:256 nt sc1
.Ld2_ss_2:
	v_cvt_pk_bf16_f32 v82, v82, v83
	v_cvt_pk_bf16_f32 v83, v84, v85
	v_cvt_pk_bf16_f32 v106, v118, v119
	v_cvt_pk_bf16_f32 v107, v120, v121
	v_cvt_pk_bf16_f32 v108, v110, v111
	s_nop 1
	v_add_u32_e32 v98, s22, v114
	v_cvt_pk_bf16_f32 v109, v112, v113
	s_bitcmp1_b32 s98, 1
	s_cbranch_scc1 .Ld2_ss_3
	buffer_store_dwordx4 v[106:109], v114, s[60:63], 0 offen nt sc1
.Ld2_ss_3:
	v_cvt_pk_bf16_f32 v84, v74, v75
	v_cvt_pk_bf16_f32 v85, v76, v77
	s_bitcmp1_b32 s98, 1
	s_cbranch_scc1 .Ld2_ss_4
	buffer_store_dwordx4 v[82:85], v98, s[60:63], 0 offen offset:256 nt sc1
.Ld2_ss_4:
	v_cvt_pk_bf16_f32 v70, v70, v71
	v_cvt_pk_bf16_f32 v71, v72, v73
	v_cvt_pk_bf16_f32 v72, v66, v67
	v_cvt_pk_bf16_f32 v50, v50, v51
	v_cvt_pk_bf16_f32 v90, v102, v103
	s_nop 1
	v_mad_u64_u32 v[82:83], s[22:23], s49, 48, v[142:143]
	s_mul_i32 s22, s49, 0xc0
	v_lshlrev_b32_e32 v83, 1, v82
	v_add_u32_e32 v66, s22, v98
	s_mul_i32 s22, s49, 0x60
	v_cvt_pk_bf16_f32 v91, v104, v105
	v_cvt_pk_bf16_f32 v92, v94, v95
	v_cvt_pk_bf16_f32 v93, v96, v97
	s_bitcmp1_b32 s98, 1
	s_cbranch_scc1 .Ld2_ss_5
	buffer_store_dwordx4 v[90:93], v98, s[60:63], 0 offen nt sc1
.Ld2_ss_5:
	v_cvt_pk_bf16_f32 v74, v86, v87
	v_cvt_pk_bf16_f32 v75, v88, v89
	v_cvt_pk_bf16_f32 v76, v78, v79
	v_cvt_pk_bf16_f32 v77, v80, v81
	s_bitcmp1_b32 s98, 1
	s_cbranch_scc1 .Ld2_ss_6
	buffer_store_dwordx4 v[74:77], v83, s[60:63], 0 offen nt sc1
.Ld2_ss_6:
	v_cvt_pk_bf16_f32 v73, v68, v69
	s_bitcmp1_b32 s98, 1
	s_cbranch_scc1 .Ld2_ss_7
	buffer_store_dwordx4 v[70:73], v83, s[60:63], 0 offen offset:256 nt sc1
.Ld2_ss_7:
	v_cvt_pk_bf16_f32 v51, v52, v53
	v_cvt_pk_bf16_f32 v52, v42, v43
	v_cvt_pk_bf16_f32 v53, v44, v45
	s_bitcmp1_b32 s98, 0
	s_cbranch_scc1 .Ld2_ss_8
	buffer_store_dwordx4 v[50:53], v66, s[60:63], 0 offen offset:256 nt sc1
.Ld2_ss_8:
	v_cvt_pk_bf16_f32 v34, v34, v35
	v_cvt_pk_bf16_f32 v62, v62, v63
	v_cvt_pk_bf16_f32 v63, v64, v65
	v_cvt_pk_bf16_f32 v64, v58, v59
	v_cvt_pk_bf16_f32 v65, v60, v61
	s_nop 1
	v_add_u32_e32 v50, s22, v82
	v_lshlrev_b32_e32 v51, 1, v50
	s_lshl_b32 s22, s49, 4
	s_bitcmp1_b32 s98, 0
	s_cbranch_scc1 .Ld2_ss_9
	buffer_store_dwordx4 v[62:65], v66, s[60:63], 0 offen nt sc1
.Ld2_ss_9:
	v_cvt_pk_bf16_f32 v35, v36, v37
	v_cvt_pk_bf16_f32 v36, v26, v27
	v_cvt_pk_bf16_f32 v37, v28, v29
	s_bitcmp1_b32 s98, 0
	s_cbranch_scc1 .Ld2_ss_10
	buffer_store_dwordx4 v[34:37], v51, s[60:63], 0 offen offset:256 nt sc1
.Ld2_ss_10:
	v_cvt_pk_bf16_f32 v18, v18, v19
	v_cvt_pk_bf16_f32 v42, v54, v55
	v_cvt_pk_bf16_f32 v43, v56, v57
	v_cvt_pk_bf16_f32 v44, v46, v47
	v_cvt_pk_bf16_f32 v45, v48, v49
	s_nop 1
	v_add_u32_e32 v34, s22, v50
	v_lshlrev_b32_e32 v35, 1, v34
	s_bitcmp1_b32 s98, 0
	s_cbranch_scc1 .Ld2_ss_11
	buffer_store_dwordx4 v[42:45], v51, s[60:63], 0 offen nt sc1
.Ld2_ss_11:
	v_cvt_pk_bf16_f32 v19, v20, v21
	v_cvt_pk_bf16_f32 v20, v10, v11
	v_cvt_pk_bf16_f32 v21, v12, v13
	s_bitcmp1_b32 s98, 0
	s_cbranch_scc1 .Ld2_ss_12
	buffer_store_dwordx4 v[18:21], v35, s[60:63], 0 offen offset:256 nt sc1
.Ld2_ss_12:
	s_andn2_b64 vcc, exec, s[20:21]
	s_mov_b64 s[20:21], -1
	v_add_lshl_u32 v18, v34, s22, 1
	v_cvt_pk_bf16_f32 v26, v38, v39
	v_cvt_pk_bf16_f32 v27, v40, v41
	v_cvt_pk_bf16_f32 v28, v30, v31
	v_cvt_pk_bf16_f32 v29, v32, v33
	s_bitcmp1_b32 s98, 0
	s_cbranch_scc1 .Ld2_ss_13
	buffer_store_dwordx4 v[26:29], v35, s[60:63], 0 offen nt sc1
.Ld2_ss_13:
	v_cvt_pk_bf16_f32 v10, v22, v23
	v_cvt_pk_bf16_f32 v11, v24, v25
	v_cvt_pk_bf16_f32 v12, v14, v15
	v_cvt_pk_bf16_f32 v13, v16, v17
	s_bitcmp1_b32 s98, 0
	s_cbranch_scc1 .Ld2_ss_14
	buffer_store_dwordx4 v[10:13], v18, s[60:63], 0 offen nt sc1
.Ld2_ss_14:
	v_cvt_pk_bf16_f32 v6, v6, v7
	v_cvt_pk_bf16_f32 v7, v8, v9
	v_cvt_pk_bf16_f32 v8, v2, v3
	v_cvt_pk_bf16_f32 v9, v4, v5
	s_bitcmp1_b32 s98, 0
	s_cbranch_scc1 .Ld2_ss_15
	buffer_store_dwordx4 v[6:9], v18, s[60:63], 0 offen offset:256 nt sc1
.Ld2_ss_15:
	s_cbranch_vccnz .LBB0_517
	s_andn2_b64 vcc, exec, s[10:11]
	s_cbranch_vccnz .LBB0_516
	s_barrier
	s_branch .LBB0_516
